# comb6 + mix-in (P3) epilogue: row rstd computed once per workgroup at the preheader and exchanged through LDS (16 PART loads per wave and unit dropped)
# speedup vs baseline: 1.0034x; 1.0034x over previous
; #define PG8_STAGE(bufoff, gbase, voff) do { _Pragma("unroll") for (int _i = 0; _i < 2; ++_i) \
;         __builtin_amdgcn_global_load_lds((const unsigned*)((const char*)(gbase) + (voff)[_i]), (LAS unsigned*)(lds + (bufoff) + ldsw + _i * 8192), 16, 0, 0); } while (0)
; #define PG8_WAIT_V(n) asm volatile("s_waitcnt vmcnt(" #n ")" ::: "memory")
; #define PG8_BAR __builtin_amdgcn_s_barrier()
; __device__ __forceinline__ void load_rstd(const float* part, int row0, int fq, float (&rs)[2][4]) {
;     ...
;         for (int m = 0; m < 4; ++m) { const float* p = part + (size_t)(row0 + ai * HALF + m * 16) * NPART + fq * 8;
;             const f32x4 a = *(const f32x4*)p, b = *(const f32x4*)(p + 4); float s = ((a[0] + a[1]) + (a[2] + a[3])) + ((b[0] + b[1]) + (b[2] + b[3]));
;             s += __shfl_xor(s, 16); s += __shfl_xor(s, 32); rs[ai][m] = rsqrtf(s * (1.0f / D) + RMS_EPS); }
; template <class Epi, class Sched, bool ALIGN_EPI>
; __device__ __forceinline__ void gemm_phase(LAS unsigned char* lds, const Gemm g, const Sched& S, const Epi& E) {
;     ...
;     const char* cA = (const char*)g.A + (size_t)cur.aoff * 2; const char* cB = (const char*)g.Bt + (size_t)cur.boff * 2;
;     PG8_STAGE(PG8_SB(0, 0), cB, voffB); PG8_STAGE(PG8_SB(0, 1), cB + hB, voffB); PG8_STAGE(PG8_SA(0, 0), cA, voffA); PG8_STAGE(PG8_SA(0, 1), cA + hA, voffA);
;     if (wr == 1) PG8_BAR;
;     PG8_WAIT_V(2); PG8_BAR;
;     PG8_STAGE(PG8_SB(1, 0), cB + kstep, voffB); PG8_STAGE(PG8_SA(1, 0), cA + kstep, voffA); PG8_STAGE(PG8_SB(1, 1), cB + hB + kstep, voffB);
;     PG8_WAIT_V(6); PG8_BAR;
.LBB0_450:
	s_mov_b64 s[40:41], 0x80
	s_and_b32 s26, s3, 3
	s_add_i32 m0, s61, 0x18000
	v_lshl_add_u64 v[6:7], v[6:7], 0, s[40:41]
	s_lshl_b32 s3, s2, 13
	s_lshl_b32 s18, s26, 12
	s_waitcnt vmcnt(2)
	s_barrier
	global_load_lds_dwordx4 v[6:7], off
	v_lshl_add_u64 v[4:5], v[4:5], 0, s[40:41]
	s_add_i32 m0, s61, 0x1a000
	s_add_i32 s69, s61, 0x8000
	s_add_i32 s71, s61, 0xa000
	global_load_lds_dwordx4 v[4:5], off
	v_lshl_add_u64 v[0:1], v[0:1], 0, s[40:41]
	s_mov_b32 m0, s69
	s_add_u32 s4, s80, 0x80080
	global_load_lds_dwordx4 v[0:1], off
	v_lshl_add_u64 v[0:1], v[2:3], 0, s[40:41]
	s_mov_b32 m0, s71
	s_addc_u32 s5, s81, 0
	global_load_lds_dwordx4 v[0:1], off
	s_add_i32 m0, s61, 0x1c000
	v_lshl_add_u64 v[0:1], s[4:5], 0, v[138:139]
	global_load_lds_dwordx4 v[0:1], off
	v_lshl_add_u64 v[0:1], s[4:5], 0, v[142:143]
	s_add_i32 m0, s61, 0x1e000
	v_lshlrev_b32_e32 v4, 2, v221
	global_load_lds_dwordx4 v[0:1], off
	v_bfe_u32 v1, v221, 4, 2
	v_and_b32_e32 v0, 15, v221
	v_lshlrev_b32_e32 v3, 4, v1
	v_lshl_or_b32 v159, s2, 6, v0
	v_lshl_or_b32 v0, v0, 6, v3
	v_and_b32_e32 v4, 32, v4
	v_bitop3_b32 v5, v0, s3, v4 bitop3:0xde
	v_lshlrev_b32_e32 v0, 6, v221
	s_movk_i32 s2, 0x3c0
	v_and_or_b32 v0, v0, s2, v3
	v_lshlrev_b32_e32 v2, 3, v1
	v_bitop3_b32 v165, s18, v0, v4 bitop3:0xf6
	v_cmp_eq_u32_e64 s[2:3], 0, v1
	v_lshlrev_b32_e32 v0, 5, v1
	v_mov_b32_e32 v1, v144
	v_lshl_add_u64 v[146:147], s[48:49], 0, v[0:1]
	v_lshlrev_b32_e32 v0, 9, v221
	v_and_b32_e32 v0, 0x70000, v0
	v_lshlrev_b32_e32 v1, 12, v10
	v_or3_b32 v0, v8, v0, v1
	v_add_u32_e32 v148, v0, v9
	v_lshlrev_b32_e32 v0, 5, v11
	v_and_b32_e32 v0, 0xf0000, v0
	s_waitcnt vmcnt(6)
	s_cmpk_lt_u32 s11, 0x100
	v_or3_b32 v0, v8, v0, v1
	s_cselect_b64 s[42:43], -1, 0
	v_add_u32_e32 v150, v0, v9
	s_add_i32 s92, 0, 0x10000
	s_add_i32 s93, 0, 0x14000
	v_mbcnt_lo_u32_b32 v0, -1, 0
	s_mov_b32 s27, s23
	s_ashr_i32 s73, s34, 31
	s_mov_b32 s90, s34
	s_ashr_i32 s91, s10, 31
	v_lshl_or_b32 v167, s26, 5, v2
	v_mov_b32_e32 v149, v144
	v_mov_b32_e32 v151, v144
	v_mov_b64_e32 v[152:153], 0x200
	v_mov_b64_e32 v[154:155], 0x1ff
	v_add_u32_e32 v173, s92, v165
	v_add_u32_e32 v175, s93, v165
	v_add_u32_e32 v181, 0, v5
	v_mbcnt_hi_u32_b32 v222, -1, v0
	s_mov_b32 s58, 0x3a000000
	s_mov_b32 s94, 0x800000
	s_mov_b32 s60, 0x3e6d3388
	s_mov_b32 s62, 0x3f07dc22
	s_mov_b32 s64, 0xbf3a00e3
	s_mov_b32 s66, 0x3f35f0e3
	s_mov_b32 s68, 0xbe11a98e
	s_mov_b32 s70, 0x3e027906
	s_mov_b32 s72, 0xbf38aa3b
	s_mov_b32 s95, 0
	s_barrier
	v_readlane_b32 s100, v254, 8
	v_lshrrev_b32_e32 v168, 1, v220
	s_lshl_b32 s101, s97, 8
	s_lshl_b32 s18, s100, 5
	s_add_i32 s101, s101, s18
	v_add_u32_e32 v168, s101, v168
	v_and_b32_e32 v169, 1, v220
	v_lshlrev_b32_e32 v169, 6, v169
	v_lshl_add_u32 v168, v168, 7, v169
	s_add_u32 s18, s14, 0xc300000
	s_addc_u32 s19, s15, 0
	global_load_dwordx4 v[176:179], v168, s[18:19]
	global_load_dwordx4 v[182:185], v168, s[18:19] offset:16
	global_load_dwordx4 v[186:189], v168, s[18:19] offset:32
	global_load_dwordx4 v[190:193], v168, s[18:19] offset:48
	v_mov_b32_e32 v169, 0x358637bd
	s_waitcnt vmcnt(0)
	v_add_f32_e32 v176, v176, v177
	v_add_f32_e32 v178, v178, v179
	v_add_f32_e32 v182, v182, v183
	v_add_f32_e32 v184, v184, v185
	v_add_f32_e32 v186, v186, v187
	v_add_f32_e32 v188, v188, v189
	v_add_f32_e32 v190, v190, v191
	v_add_f32_e32 v192, v192, v193
	v_add_f32_e32 v176, v176, v178
	v_add_f32_e32 v182, v182, v184
	v_add_f32_e32 v186, v186, v188
	v_add_f32_e32 v190, v190, v192
	v_add_f32_e32 v176, v176, v182
	v_add_f32_e32 v186, v186, v190
	v_add_f32_e32 v176, v176, v186
	s_nop 1
	v_add_f32_dpp v182, v176, v176 quad_perm:[1,0,3,2] row_mask:0xf bank_mask:0xf
	v_fmamk_f32 v182, v182, 0x3a000000, v169
	v_rsq_f32_e32 v182, v182
	s_lshl_b32 s101, s100, 7
	s_add_i32 s101, s101, 0x21000
	v_lshrrev_b32_e32 v168, 1, v220
	v_lshl_add_u32 v168, v168, 2, s101
	ds_write_b32 v168, v182
	s_branch .LBB0_453

; __device__ __forceinline__ void load_rstd(const float* part, int row0, int fq, float (&rs)[2][4]) {
; #pragma unroll
;     for (int ai = 0; ai < 2; ++ai)
; #pragma unroll
;         for (int m = 0; m < 4; ++m) { const float* p = part + (size_t)(row0 + ai * HALF + m * 16) * NPART + fq * 8;
;             const f32x4 a = *(const f32x4*)p, b = *(const f32x4*)(p + 4); float s = ((a[0] + a[1]) + (a[2] + a[3])) + ((b[0] + b[1]) + (b[2] + b[3]));
;             s += __shfl_xor(s, 16); s += __shfl_xor(s, 32); rs[ai][m] = rsqrtf(s * (1.0f / D) + RMS_EPS); }
.LBB0_469:
	v_and_b32_e32 v129, 64, v222
	v_xor_b32_e32 v128, 16, v222
	v_add_u32_e32 v129, 64, v129
	v_cmp_lt_i32_e32 vcc, v128, v129
	v_lshl_add_u32 v198, s97, 8, v159
	v_ashrrev_i32_e32 v199, 31, v198
	v_cndmask_b32_e32 v128, v222, v128, vcc
	v_lshlrev_b32_e32 v224, 2, v128
	v_xor_b32_e32 v128, 32, v222
	v_cmp_lt_i32_e32 vcc, v128, v129
	v_lshlrev_b64 v[196:197], 7, v[198:199]
	v_lshl_add_u64 v[132:133], v[146:147], 0, v[196:197]
	v_cndmask_b32_e32 v128, v222, v128, vcc
	v_lshlrev_b32_e32 v223, 2, v128
	s_nop 0
	s_nop 0
	s_nop 0
	s_mov_b32 s6, 0x358637bd
	v_mov_b64_e32 v[200:201], s[6:7]
	s_cmp_gt_i32 s96, 7
	s_nop 0
	v_mov_b32_e32 v156, v128
	v_mov_b32_e32 v157, v132
	v_mov_b32_e32 v132, v129
	v_pk_add_f32 v[128:129], v[156:157], v[132:133]
	v_or_b32_e32 v156, 16, v198
	v_ashrrev_i32_e32 v157, 31, v156
	v_mov_b32_e32 v132, v130
	v_mov_b32_e32 v133, v134
	v_mov_b32_e32 v134, v131
	v_lshlrev_b64 v[194:195], 7, v[156:157]
	v_pk_add_f32 v[130:131], v[132:133], v[134:135]
	v_lshl_add_u64 v[132:133], v[146:147], 0, v[194:195]
	v_pk_add_f32 v[160:161], v[128:129], v[130:131]
	s_nop 0
	s_nop 0
	s_nop 0
	s_nop 0
	v_mov_b32_e32 v162, v128
	s_nop 0
	v_mov_b32_e32 v163, v132
	v_mov_b32_e32 v132, v129
	v_pk_add_f32 v[128:129], v[162:163], v[132:133]
	v_mov_b32_e32 v132, v130
	v_mov_b32_e32 v133, v134
	v_mov_b32_e32 v134, v131
	v_pk_add_f32 v[130:131], v[132:133], v[134:135]
	v_or_b32_e32 v162, 32, v198
	v_pk_add_f32 v[128:129], v[128:129], v[130:131]
	v_mov_b32_e32 v131, v160
	v_mov_b32_e32 v130, v128
	v_mov_b32_e32 v160, v129
	v_pk_add_f32 v[128:129], v[130:131], v[160:161]
	ds_bpermute_b32 v131, v224, v129
	ds_bpermute_b32 v130, v224, v128
	v_ashrrev_i32_e32 v163, 31, v162
	v_lshlrev_b64 v[192:193], 7, v[162:163]
	v_lshl_add_u64 v[132:133], v[146:147], 0, v[192:193]
	s_waitcnt lgkmcnt(0)
	v_pk_add_f32 v[128:129], v[128:129], v[130:131]
	ds_bpermute_b32 v131, v223, v129
	ds_bpermute_b32 v130, v223, v128
	s_waitcnt lgkmcnt(0)
	v_pk_add_f32 v[128:129], v[128:129], v[130:131]
	s_nop 0
	v_pk_fma_f32 v[128:129], v[128:129], s[58:59], v[200:201] op_sel_hi:[1,0,0]
	s_nop 0
	v_mul_f32_e32 v130, 0x4b800000, v129
	v_cmp_gt_f32_e64 s[6:7], s94, v129
	v_cmp_gt_f32_e32 vcc, s94, v128
	s_nop 0
	v_cndmask_b32_e64 v129, v129, v130, s[6:7]
	v_rsq_f32_e32 v129, v129
	s_nop 0
	v_mul_f32_e32 v130, 0x45800000, v129
	v_cndmask_b32_e64 v166, v129, v130, s[6:7]
	v_mul_f32_e32 v129, 0x4b800000, v128
	v_cndmask_b32_e32 v128, v128, v129, vcc
	v_rsq_f32_e32 v128, v128
	s_nop 0
	v_mul_f32_e32 v129, 0x45800000, v128
	v_cndmask_b32_e32 v158, v128, v129, vcc
	s_nop 0
	s_nop 0
	s_nop 0
	s_nop 0
	v_mov_b32_e32 v160, v128
	s_nop 0
	v_mov_b32_e32 v161, v132
	v_mov_b32_e32 v132, v129
	v_pk_add_f32 v[128:129], v[160:161], v[132:133]
	v_or_b32_e32 v160, 48, v198
	v_ashrrev_i32_e32 v161, 31, v160
	v_mov_b32_e32 v132, v130
	v_mov_b32_e32 v133, v134
	v_mov_b32_e32 v134, v131
	v_lshlrev_b64 v[190:191], 7, v[160:161]
	v_pk_add_f32 v[130:131], v[132:133], v[134:135]
	v_lshl_add_u64 v[132:133], v[146:147], 0, v[190:191]
	v_pk_add_f32 v[168:169], v[128:129], v[130:131]
	s_nop 0
	s_nop 0
	s_nop 0
	s_nop 0
	v_mov_b32_e32 v170, v128
	s_nop 0
	v_mov_b32_e32 v171, v132
	v_mov_b32_e32 v132, v129
	v_pk_add_f32 v[128:129], v[170:171], v[132:133]
	v_mov_b32_e32 v132, v130
	v_mov_b32_e32 v133, v134
	v_mov_b32_e32 v134, v131
	v_pk_add_f32 v[130:131], v[132:133], v[134:135]
	v_add_u32_e32 v170, 0x80, v198
	v_pk_add_f32 v[128:129], v[128:129], v[130:131]
	v_mov_b32_e32 v131, v168
	v_mov_b32_e32 v130, v128
	v_mov_b32_e32 v168, v129
	v_pk_add_f32 v[128:129], v[130:131], v[168:169]
	ds_bpermute_b32 v131, v224, v129
	ds_bpermute_b32 v130, v224, v128
	v_ashrrev_i32_e32 v171, 31, v170
	v_lshlrev_b64 v[188:189], 7, v[170:171]
	v_lshl_add_u64 v[132:133], v[146:147], 0, v[188:189]
	s_waitcnt lgkmcnt(0)
	v_pk_add_f32 v[128:129], v[128:129], v[130:131]
	ds_bpermute_b32 v131, v223, v129
	ds_bpermute_b32 v130, v223, v128
	s_waitcnt lgkmcnt(0)
	v_pk_add_f32 v[128:129], v[128:129], v[130:131]
	s_nop 0
	v_pk_fma_f32 v[128:129], v[128:129], s[58:59], v[200:201] op_sel_hi:[1,0,0]
	s_nop 0
	v_mul_f32_e32 v130, 0x4b800000, v129
	v_cmp_gt_f32_e64 s[6:7], s94, v129
	v_cmp_gt_f32_e32 vcc, s94, v128
	s_nop 0
	v_cndmask_b32_e64 v129, v129, v130, s[6:7]
	v_rsq_f32_e32 v129, v129
	s_nop 0
	v_mul_f32_e32 v130, 0x45800000, v129
	v_cndmask_b32_e64 v172, v129, v130, s[6:7]
	v_mul_f32_e32 v129, 0x4b800000, v128
	v_cndmask_b32_e32 v128, v128, v129, vcc
	v_rsq_f32_e32 v128, v128
	s_nop 0
	v_mul_f32_e32 v129, 0x45800000, v128
	v_cndmask_b32_e32 v164, v128, v129, vcc
	s_nop 0
	s_nop 0
	s_nop 0
	s_nop 0
	v_mov_b32_e32 v168, v128
	s_nop 0
	v_mov_b32_e32 v169, v132
	v_mov_b32_e32 v132, v129
	v_pk_add_f32 v[128:129], v[168:169], v[132:133]
	v_add_u32_e32 v168, 0x90, v198
	v_ashrrev_i32_e32 v169, 31, v168
	v_mov_b32_e32 v132, v130
	v_mov_b32_e32 v133, v134
	v_mov_b32_e32 v134, v131
	v_lshlrev_b64 v[186:187], 7, v[168:169]
	v_pk_add_f32 v[130:131], v[132:133], v[134:135]
	v_lshl_add_u64 v[132:133], v[146:147], 0, v[186:187]
	v_pk_add_f32 v[176:177], v[128:129], v[130:131]
	s_nop 0
	s_nop 0
	s_nop 0
	s_nop 0
	v_mov_b32_e32 v178, v128
	s_nop 0
	v_mov_b32_e32 v179, v132
	v_mov_b32_e32 v132, v129
	v_pk_add_f32 v[128:129], v[178:179], v[132:133]
	v_mov_b32_e32 v132, v130
	v_mov_b32_e32 v133, v134
	v_mov_b32_e32 v134, v131
	v_pk_add_f32 v[130:131], v[132:133], v[134:135]
	v_add_u32_e32 v178, 0xa0, v198
	v_pk_add_f32 v[128:129], v[128:129], v[130:131]
	v_mov_b32_e32 v131, v176
	v_mov_b32_e32 v130, v128
	v_mov_b32_e32 v176, v129
	v_pk_add_f32 v[128:129], v[130:131], v[176:177]
	ds_bpermute_b32 v131, v224, v129
	ds_bpermute_b32 v130, v224, v128
	v_ashrrev_i32_e32 v179, 31, v178
	v_lshlrev_b64 v[184:185], 7, v[178:179]
	v_lshl_add_u64 v[132:133], v[146:147], 0, v[184:185]
	s_waitcnt lgkmcnt(0)
; __device__ __forceinline__ unsigned cvt_pk_bf16(float lo, float hi) { unsigned r; asm volatile("v_cvt_pk_bf16_f32 %0, %1, %2" : "=v"(r) : "v"(lo), "v"(hi)); return r; }
; __device__ __forceinline__ f32x4 gelu4(f32x4 v) { f32x2 a = gelu_pk((f32x2){v[0], v[1]}), b = gelu_pk((f32x2){v[2], v[3]}); return (f32x4){a.x, a.y, b.x, b.y}; }
; __device__ __forceinline__ void load_rstd(const float* part, int row0, int fq, float (&rs)[2][4]) {
;     ...
;         for (int m = 0; m < 4; ++m) { const float* p = part + (size_t)(row0 + ai * HALF + m * 16) * NPART + fq * 8;
;             const f32x4 a = *(const f32x4*)p, b = *(const f32x4*)(p + 4); float s = ((a[0] + a[1]) + (a[2] + a[3])) + ((b[0] + b[1]) + (b[2] + b[3]));
;             s += __shfl_xor(s, 16); s += __shfl_xor(s, 32); rs[ai][m] = rsqrtf(s * (1.0f / D) + RMS_EPS); }
;     __device__ __forceinline__ void operator()(const f32x4 (&acc)[2][2][4][2], const Unit& u, int wr, int wc, int fr, int fq) const {
;     ...
;             const bool isv = u.pn >= 12; bf16_t* dst = isv ? VB : UB; const int tq = isv ? u.pn - 12 : u.pn - 8;
;             const int col0 = tq * BM + wc * 32 + 8 * fq;
; #pragma unroll
;             for (int ai = 0; ai < 2; ++ai)
; #pragma unroll
;                 for (int m = 0; m < 4; ++m) { const float sc = rs[ai][m]; const int row = row0 + ai * HALF + m * 16; float s1 = 0.f, s2 = 0.f;
; #pragma unroll
;                     for (int bj = 0; bj < 2; ++bj) { const f32x4 v0 = gelu4(acc[ai][bj][m][0] * sc), v1 = gelu4(acc[ai][bj][m][1] * sc);
;                         s1 += ((v0[0] + v0[1]) + (v0[2] + v0[3])) + ((v1[0] + v1[1]) + (v1[2] + v1[3]));
;                         s2 += ((v0[0] * v0[0] + v0[1] * v0[1]) + (v0[2] * v0[2] + v0[3] * v0[3])) + ((v1[0] * v1[0] + v1[1] * v1[1]) + (v1[2] * v1[2] + v1[3] * v1[3]));
;                         u32x4 w; w.x = cvt_pk_bf16(v0[0], v0[1]); w.y = cvt_pk_bf16(v0[2], v0[3]); w.z = cvt_pk_bf16(v1[0], v1[1]); w.w = cvt_pk_bf16(v1[2], v1[3]);
;                         *(u32x4*)(dst + (size_t)row * CCH + col0 + bj * HALF) = w; }
	v_pk_add_f32 v[128:129], v[128:129], v[130:131]
	ds_bpermute_b32 v131, v223, v129
	ds_bpermute_b32 v130, v223, v128
	s_waitcnt lgkmcnt(0)
	v_pk_add_f32 v[128:129], v[128:129], v[130:131]
	s_nop 0
	v_pk_fma_f32 v[128:129], v[128:129], s[58:59], v[200:201] op_sel_hi:[1,0,0]
	s_nop 0
	v_mul_f32_e32 v130, 0x4b800000, v129
	v_cmp_gt_f32_e64 s[6:7], s94, v129
	v_cmp_gt_f32_e32 vcc, s94, v128
	s_nop 0
	v_cndmask_b32_e64 v129, v129, v130, s[6:7]
	v_rsq_f32_e32 v129, v129
	s_nop 0
	v_mul_f32_e32 v130, 0x45800000, v129
	v_cndmask_b32_e64 v180, v129, v130, s[6:7]
	v_mul_f32_e32 v129, 0x4b800000, v128
	v_cndmask_b32_e32 v128, v128, v129, vcc
	v_rsq_f32_e32 v128, v128
	s_nop 0
	v_mul_f32_e32 v129, 0x45800000, v128
	v_cndmask_b32_e32 v174, v128, v129, vcc
	s_nop 0
	s_nop 0
	s_nop 0
	s_nop 0
	v_mov_b32_e32 v176, v128
	s_nop 0
	v_mov_b32_e32 v177, v132
	v_mov_b32_e32 v132, v129
	v_pk_add_f32 v[128:129], v[176:177], v[132:133]
	v_add_u32_e32 v176, 0xb0, v198
	v_mov_b32_e32 v132, v130
	v_mov_b32_e32 v133, v134
	v_mov_b32_e32 v134, v131
	v_ashrrev_i32_e32 v177, 31, v176
	v_pk_add_f32 v[130:131], v[132:133], v[134:135]
	v_lshlrev_b64 v[182:183], 7, v[176:177]
	v_pk_add_f32 v[202:203], v[128:129], v[130:131]
	v_lshl_add_u64 v[128:129], v[146:147], 0, v[182:183]
	s_nop 0
	s_nop 0
	s_nop 0
	s_nop 0
	v_mov_b32_e32 v204, v132
	s_nop 0
	v_mov_b32_e32 v205, v128
	v_mov_b32_e32 v128, v133
	v_mov_b32_e32 v132, v134
	v_mov_b32_e32 v133, v130
	v_mov_b32_e32 v130, v135
	v_pk_add_f32 v[128:129], v[204:205], v[128:129]
	v_pk_add_f32 v[130:131], v[132:133], v[130:131]
	v_lshlrev_b64 v[132:133], 11, v[198:199]
	v_pk_add_f32 v[128:129], v[128:129], v[130:131]
	v_mov_b32_e32 v131, v202
	v_mov_b32_e32 v130, v128
	v_mov_b32_e32 v202, v129
	v_pk_add_f32 v[128:129], v[130:131], v[202:203]
	ds_bpermute_b32 v131, v224, v129
	ds_bpermute_b32 v130, v224, v128
	s_waitcnt lgkmcnt(0)
	v_pk_add_f32 v[128:129], v[128:129], v[130:131]
	ds_bpermute_b32 v131, v223, v129
	ds_bpermute_b32 v130, v223, v128
	s_waitcnt lgkmcnt(0)
	v_pk_add_f32 v[128:129], v[128:129], v[130:131]
	s_nop 0
	v_pk_fma_f32 v[128:129], v[128:129], s[58:59], v[200:201] op_sel_hi:[1,0,0]
	s_nop 0
	v_mul_f32_e32 v130, 0x4b800000, v129
	v_cmp_gt_f32_e64 s[6:7], s94, v129
	v_cmp_gt_f32_e32 vcc, s94, v128
	s_nop 0
	v_cndmask_b32_e64 v129, v129, v130, s[6:7]
	v_rsq_f32_e32 v129, v129
	s_nop 0
	v_mul_f32_e32 v130, 0x45800000, v129
	v_cndmask_b32_e64 v130, v129, v130, s[6:7]
	v_mul_f32_e32 v129, 0x4b800000, v128
	v_cndmask_b32_e32 v128, v128, v129, vcc
	v_rsq_f32_e32 v128, v128
	s_mov_b64 s[6:7], -1
	v_mul_f32_e32 v129, 0x45800000, v128
	v_cndmask_b32_e32 v128, v128, v129, vcc
	v_lshlrev_b32_e32 v131, 2, v159
	v_add_u32_e32 v131, 0x21000, v131
	ds_read_b32 v166, v131
	ds_read_b32 v158, v131 offset:64
	ds_read_b32 v172, v131 offset:128
	ds_read_b32 v164, v131 offset:192
	ds_read_b32 v180, v131 offset:512
	ds_read_b32 v174, v131 offset:576
	ds_read_b32 v130, v131 offset:640
	ds_read_b32 v128, v131 offset:704
	s_waitcnt lgkmcnt(0)
	s_cbranch_scc0 .LBB0_504
	s_cmp_gt_u32 s96, 11
	s_cselect_b64 s[82:83], -1, 0
	s_and_b64 s[6:7], s[82:83], exec
	s_cselect_b32 s18, s36, s88
	s_cselect_b32 s19, s37, s89
	s_add_i32 s33, s96, -12
	s_add_i32 s44, s96, -8
	s_and_b64 s[6:7], s[82:83], exec
	s_cselect_b32 s44, s33, s44
	v_lshl_or_b32 v198, s44, 8, v167
	v_mov_b32_e32 v134, s18
	v_mov_b32_e32 v135, s19
	v_ashrrev_i32_e32 v199, 31, v198
	v_pk_mul_f32 v[202:203], v[124:125], v[166:167] op_sel_hi:[1,0]
	v_lshl_add_u64 v[134:135], v[198:199], 1, v[134:135]
	v_and_b32_e32 v199, 0x7fffffff, v203
	v_and_b32_e32 v198, 0x7fffffff, v202
	v_pk_fma_f32 v[198:199], v[198:199], s[60:61], 1.0 op_sel_hi:[1,0,0]
	v_pk_mul_f32 v[204:205], v[126:127], v[166:167] op_sel_hi:[1,0]
	v_rcp_f32_e32 v200, v198
	v_rcp_f32_e32 v201, v199
	v_mov_b64_e32 v[226:227], s[64:65]
	v_pk_mul_f32 v[208:209], v[202:203], v[202:203]
	v_and_b32_e32 v211, 0x7fffffff, v205
	v_pk_fma_f32 v[206:207], v[200:201], s[62:63], v[226:227] op_sel_hi:[1,0,0]
	v_pk_mul_f32 v[208:209], v[208:209], s[72:73] op_sel_hi:[1,0]
	v_and_b32_e32 v210, 0x7fffffff, v204
	v_pk_fma_f32 v[206:207], v[200:201], v[206:207], s[66:67] op_sel_hi:[1,1,0]
	v_exp_f32_e32 v208, v208
	v_exp_f32_e32 v209, v209
	v_pk_fma_f32 v[210:211], v[210:211], s[60:61], 1.0 op_sel_hi:[1,0,0]
	v_pk_fma_f32 v[206:207], v[200:201], v[206:207], s[68:69] op_sel_hi:[1,1,0]
	v_rcp_f32_e32 v210, v210
	v_rcp_f32_e32 v211, v211
	v_pk_fma_f32 v[206:207], v[200:201], v[206:207], s[70:71] op_sel_hi:[1,1,0]
	v_pk_mul_f32 v[228:229], v[118:119], v[166:167] op_sel_hi:[1,0]
	v_pk_mul_f32 v[200:201], v[200:201], v[206:207]
	v_pk_mul_f32 v[206:207], v[204:205], v[204:205]
	v_pk_mul_f32 v[200:201], v[208:209], v[200:201]
	v_pk_mul_f32 v[206:207], v[206:207], s[72:73] op_sel_hi:[1,0]
	v_pk_mul_f32 v[208:209], v[202:203], v[200:201]
	v_pk_fma_f32 v[212:213], v[202:203], v[200:201], v[202:203] neg_lo:[1,0,0] neg_hi:[1,0,0]
	v_pk_fma_f32 v[200:201], v[210:211], s[62:63], v[226:227] op_sel_hi:[1,0,0]
	v_exp_f32_e32 v206, v206
	v_pk_fma_f32 v[200:201], v[210:211], v[200:201], s[66:67] op_sel_hi:[1,1,0]
	v_exp_f32_e32 v207, v207
	v_pk_fma_f32 v[200:201], v[210:211], v[200:201], s[68:69] op_sel_hi:[1,1,0]
	v_and_b32_e32 v231, 0x7fffffff, v229
	v_pk_fma_f32 v[200:201], v[210:211], v[200:201], s[70:71] op_sel_hi:[1,1,0]
	v_and_b32_e32 v230, 0x7fffffff, v228
	v_pk_mul_f32 v[200:201], v[210:211], v[200:201]
	v_pk_fma_f32 v[230:231], v[230:231], s[60:61], 1.0 op_sel_hi:[1,0,0]
	v_pk_mul_f32 v[200:201], v[206:207], v[200:201]
	v_pk_mul_f32 v[206:207], v[116:117], v[166:167] op_sel_hi:[1,0]
	v_pk_mul_f32 v[214:215], v[204:205], v[200:201]
	v_and_b32_e32 v211, 0x7fffffff, v207
; __device__ __forceinline__ unsigned cvt_pk_bf16(float lo, float hi) { unsigned r; asm volatile("v_cvt_pk_bf16_f32 %0, %1, %2" : "=v"(r) : "v"(lo), "v"(hi)); return r; }
; __device__ __forceinline__ f32x2 gelu_pk(f32x2 v) {
;     const f32x2 av = __builtin_elementwise_abs(v), d = av * 0.2316418882f + 1.0f;
;     f32x2 t; t.x = __builtin_amdgcn_rcpf(d.x); t.y = __builtin_amdgcn_rcpf(d.y);
;     f32x2 q = t * 0.5307027145f + (-0.7265760135f); q = q * t + 0.7107068705f; q = q * t + (-0.142248368f); q = q * t + 0.127414796f; q = q * t;
;     const f32x2 s = (v * v) * (-0.72134752044f);
;     f32x2 e; e.x = __builtin_amdgcn_exp2f(s.x); e.y = __builtin_amdgcn_exp2f(s.y);
;     const f32x2 m = v * (q * e), r = v - m;
;     f32x2 o; o.x = v.x < 0.f ? m.x : r.x; o.y = v.y < 0.f ? m.y : r.y; return o;
; }
; __device__ __forceinline__ f32x4 gelu4(f32x4 v) { f32x2 a = gelu_pk((f32x2){v[0], v[1]}), b = gelu_pk((f32x2){v[2], v[3]}); return (f32x4){a.x, a.y, b.x, b.y}; }
;     __device__ __forceinline__ void operator()(const f32x4 (&acc)[2][2][4][2], const Unit& u, int wr, int wc, int fr, int fq) const {
;     ...
;                     for (int bj = 0; bj < 2; ++bj) { const f32x4 v0 = gelu4(acc[ai][bj][m][0] * sc), v1 = gelu4(acc[ai][bj][m][1] * sc);
;                         s1 += ((v0[0] + v0[1]) + (v0[2] + v0[3])) + ((v1[0] + v1[1]) + (v1[2] + v1[3]));
;                         s2 += ((v0[0] * v0[0] + v0[1] * v0[1]) + (v0[2] * v0[2] + v0[3] * v0[3])) + ((v1[0] * v1[0] + v1[1] * v1[1]) + (v1[2] * v1[2] + v1[3] * v1[3]));
;                         u32x4 w; w.x = cvt_pk_bf16(v0[0], v0[1]); w.y = cvt_pk_bf16(v0[2], v0[3]); w.z = cvt_pk_bf16(v1[0], v1[1]); w.w = cvt_pk_bf16(v1[2], v1[3]);
;                         *(u32x4*)(dst + (size_t)row * CCH + col0 + bj * HALF) = w; }
	v_and_b32_e32 v210, 0x7fffffff, v206
	v_pk_fma_f32 v[210:211], v[210:211], s[60:61], 1.0 op_sel_hi:[1,0,0]
	v_pk_mul_f32 v[216:217], v[206:207], v[206:207]
	v_rcp_f32_e32 v210, v210
	v_rcp_f32_e32 v211, v211
	v_pk_fma_f32 v[218:219], v[204:205], v[200:201], v[204:205] neg_lo:[1,0,0] neg_hi:[1,0,0]
	v_pk_mul_f32 v[216:217], v[216:217], s[72:73] op_sel_hi:[1,0]
	v_rcp_f32_e32 v230, v230
	v_pk_fma_f32 v[200:201], v[210:211], s[62:63], v[226:227] op_sel_hi:[1,0,0]
	v_exp_f32_e32 v216, v216
	v_pk_fma_f32 v[200:201], v[210:211], v[200:201], s[66:67] op_sel_hi:[1,1,0]
	v_exp_f32_e32 v217, v217
	v_pk_fma_f32 v[200:201], v[210:211], v[200:201], s[68:69] op_sel_hi:[1,1,0]
	v_rcp_f32_e32 v231, v231
	v_pk_fma_f32 v[200:201], v[210:211], v[200:201], s[70:71] op_sel_hi:[1,1,0]
	v_pk_mul_f32 v[238:239], v[122:123], v[166:167] op_sel_hi:[1,0]
	v_pk_mul_f32 v[200:201], v[210:211], v[200:201]
	v_pk_mul_f32 v[210:211], v[228:229], v[228:229]
	v_pk_mul_f32 v[200:201], v[216:217], v[200:201]
	v_pk_mul_f32 v[210:211], v[210:211], s[72:73] op_sel_hi:[1,0]
	v_pk_mul_f32 v[232:233], v[206:207], v[200:201]
	v_pk_fma_f32 v[234:235], v[206:207], v[200:201], v[206:207] neg_lo:[1,0,0] neg_hi:[1,0,0]
	v_pk_fma_f32 v[200:201], v[230:231], s[62:63], v[226:227] op_sel_hi:[1,0,0]
	v_exp_f32_e32 v210, v210
	v_pk_fma_f32 v[200:201], v[230:231], v[200:201], s[66:67] op_sel_hi:[1,1,0]
	v_exp_f32_e32 v211, v211
	v_pk_fma_f32 v[200:201], v[230:231], v[200:201], s[68:69] op_sel_hi:[1,1,0]
	v_and_b32_e32 v243, 0x7fffffff, v239
	v_pk_fma_f32 v[200:201], v[230:231], v[200:201], s[70:71] op_sel_hi:[1,1,0]
	v_and_b32_e32 v242, 0x7fffffff, v238
	v_pk_mul_f32 v[200:201], v[230:231], v[200:201]
	v_pk_fma_f32 v[242:243], v[242:243], s[60:61], 1.0 op_sel_hi:[1,0,0]
	v_pk_mul_f32 v[200:201], v[210:211], v[200:201]
	v_pk_mul_f32 v[210:211], v[120:121], v[166:167] op_sel_hi:[1,0]
	v_pk_mul_f32 v[230:231], v[228:229], v[200:201]
	v_and_b32_e32 v217, 0x7fffffff, v211
	v_and_b32_e32 v216, 0x7fffffff, v210
	v_pk_fma_f32 v[216:217], v[216:217], s[60:61], 1.0 op_sel_hi:[1,0,0]
	v_pk_mul_f32 v[240:241], v[210:211], v[210:211]
	v_rcp_f32_e32 v216, v216
	v_rcp_f32_e32 v217, v217
	v_pk_fma_f32 v[236:237], v[228:229], v[200:201], v[228:229] neg_lo:[1,0,0] neg_hi:[1,0,0]
	v_pk_mul_f32 v[240:241], v[240:241], s[72:73] op_sel_hi:[1,0]
	v_rcp_f32_e32 v242, v242
	v_pk_fma_f32 v[200:201], v[216:217], s[62:63], v[226:227] op_sel_hi:[1,0,0]
	v_exp_f32_e32 v240, v240
	v_pk_fma_f32 v[200:201], v[216:217], v[200:201], s[66:67] op_sel_hi:[1,1,0]
	v_exp_f32_e32 v241, v241
	v_pk_fma_f32 v[200:201], v[216:217], v[200:201], s[68:69] op_sel_hi:[1,1,0]
	v_rcp_f32_e32 v243, v243
	v_pk_fma_f32 v[200:201], v[216:217], v[200:201], s[70:71] op_sel_hi:[1,1,0]
	v_cmp_gt_f32_e32 vcc, 0, v202
	v_pk_mul_f32 v[200:201], v[216:217], v[200:201]
	v_pk_mul_f32 v[216:217], v[238:239], v[238:239]
	v_pk_mul_f32 v[200:201], v[240:241], v[200:201]
	v_pk_mul_f32 v[216:217], v[216:217], s[72:73] op_sel_hi:[1,0]
	v_pk_mul_f32 v[240:241], v[210:211], v[200:201]
	v_pk_fma_f32 v[244:245], v[210:211], v[200:201], v[210:211] neg_lo:[1,0,0] neg_hi:[1,0,0]
	v_pk_fma_f32 v[200:201], v[242:243], s[62:63], v[226:227] op_sel_hi:[1,0,0]
	v_exp_f32_e32 v216, v216
	v_pk_fma_f32 v[200:201], v[242:243], v[200:201], s[66:67] op_sel_hi:[1,1,0]
	v_exp_f32_e32 v217, v217
	v_pk_fma_f32 v[200:201], v[242:243], v[200:201], s[68:69] op_sel_hi:[1,1,0]
	v_lshl_add_u64 v[198:199], v[134:135], 0, v[132:133]
	v_pk_fma_f32 v[200:201], v[242:243], v[200:201], s[70:71] op_sel_hi:[1,1,0]
	s_lshl_b32 s6, s33, 2
	v_pk_mul_f32 v[200:201], v[242:243], v[200:201]
	s_ashr_i32 s7, s6, 31
	v_pk_mul_f32 v[200:201], v[216:217], v[200:201]
	s_or_b64 s[80:81], s[6:7], s[26:27]
	v_pk_mul_f32 v[242:243], v[238:239], v[200:201]
	v_pk_fma_f32 v[246:247], v[238:239], v[200:201], v[238:239] neg_lo:[1,0,0] neg_hi:[1,0,0]
	v_cndmask_b32_e32 v200, v212, v208, vcc
	v_cmp_gt_f32_e32 vcc, 0, v210
	s_cmp_lt_u32 s96, 12
	s_nop 0
	v_cndmask_b32_e32 v201, v244, v240, vcc
	v_cmp_gt_f32_e32 vcc, 0, v203
	s_nop 1
	v_cndmask_b32_e32 v208, v213, v209, vcc
	v_cmp_gt_f32_e32 vcc, 0, v204
	v_cvt_pk_bf16_f32 v216, v200, v208
	s_nop 1
	v_cndmask_b32_e32 v202, v218, v214, vcc
	v_cmp_gt_f32_e32 vcc, 0, v211
	s_nop 1
	v_cndmask_b32_e32 v203, v245, v241, vcc
	v_cmp_gt_f32_e32 vcc, 0, v205
	s_nop 1
	v_cndmask_b32_e32 v210, v219, v215, vcc
	v_cmp_gt_f32_e32 vcc, 0, v206
	v_cvt_pk_bf16_f32 v217, v202, v210
	s_nop 1
	v_cndmask_b32_e32 v204, v234, v232, vcc
	v_cmp_gt_f32_e32 vcc, 0, v238
	s_nop 1
	v_cndmask_b32_e32 v205, v246, v242, vcc
	v_cmp_gt_f32_e32 vcc, 0, v207
	s_nop 1
	v_cndmask_b32_e32 v212, v235, v233, vcc
	v_cmp_gt_f32_e32 vcc, 0, v228
	v_cvt_pk_bf16_f32 v218, v204, v212
	s_nop 1
	v_cndmask_b32_e32 v206, v236, v230, vcc
	v_cmp_gt_f32_e32 vcc, 0, v239
	s_nop 1
	v_cndmask_b32_e32 v207, v247, v243, vcc
	v_cmp_gt_f32_e32 vcc, 0, v229
	v_pk_mul_f32 v[228:229], v[112:113], v[166:167] op_sel_hi:[1,0]
	s_nop 0
	v_cndmask_b32_e32 v214, v237, v231, vcc
	v_and_b32_e32 v231, 0x7fffffff, v229
	v_and_b32_e32 v230, 0x7fffffff, v228
	v_pk_fma_f32 v[230:231], v[230:231], s[60:61], 1.0 op_sel_hi:[1,0,0]
	v_cvt_pk_bf16_f32 v219, v206, v214
; __device__ __forceinline__ unsigned cvt_pk_bf16(float lo, float hi) { unsigned r; asm volatile("v_cvt_pk_bf16_f32 %0, %1, %2" : "=v"(r) : "v"(lo), "v"(hi)); return r; }
; __device__ __forceinline__ f32x4 gelu4(f32x4 v) { f32x2 a = gelu_pk((f32x2){v[0], v[1]}), b = gelu_pk((f32x2){v[2], v[3]}); return (f32x4){a.x, a.y, b.x, b.y}; }
;     __device__ __forceinline__ void operator()(const f32x4 (&acc)[2][2][4][2], const Unit& u, int wr, int wc, int fr, int fq) const {
;     ...
;                     for (int bj = 0; bj < 2; ++bj) { const f32x4 v0 = gelu4(acc[ai][bj][m][0] * sc), v1 = gelu4(acc[ai][bj][m][1] * sc);
;                         s1 += ((v0[0] + v0[1]) + (v0[2] + v0[3])) + ((v1[0] + v1[1]) + (v1[2] + v1[3]));
;                         s2 += ((v0[0] * v0[0] + v0[1] * v0[1]) + (v0[2] * v0[2] + v0[3] * v0[3])) + ((v1[0] * v1[0] + v1[1] * v1[1]) + (v1[2] * v1[2] + v1[3] * v1[3]));
;                         u32x4 w; w.x = cvt_pk_bf16(v0[0], v0[1]); w.y = cvt_pk_bf16(v0[2], v0[3]); w.z = cvt_pk_bf16(v1[0], v1[1]); w.w = cvt_pk_bf16(v1[2], v1[3]);
;                         *(u32x4*)(dst + (size_t)row * CCH + col0 + bj * HALF) = w; }
;                     if (isv) { s1 += __shfl_xor(s1, 16); s1 += __shfl_xor(s1, 32); s2 += __shfl_xor(s2, 16); s2 += __shfl_xor(s2, 32);
;                         if (fq == 0) *(f32x2*)(vstat + ((size_t)row * 16 + tq * 4 + wc) * 2) = (f32x2){s1, s2}; } }
	global_store_dwordx4 v[198:199], v[216:219], off
	v_rcp_f32_e32 v230, v230
	v_rcp_f32_e32 v231, v231
	v_pk_mul_f32 v[218:219], v[114:115], v[166:167] op_sel_hi:[1,0]
	v_pk_mul_f32 v[232:233], v[228:229], v[228:229]
	v_and_b32_e32 v235, 0x7fffffff, v219
	v_pk_fma_f32 v[216:217], v[230:231], s[62:63], v[226:227] op_sel_hi:[1,0,0]
	v_pk_mul_f32 v[232:233], v[232:233], s[72:73] op_sel_hi:[1,0]
	v_and_b32_e32 v234, 0x7fffffff, v218
	v_pk_fma_f32 v[216:217], v[230:231], v[216:217], s[66:67] op_sel_hi:[1,1,0]
	v_exp_f32_e32 v232, v232
	v_exp_f32_e32 v233, v233
	v_pk_fma_f32 v[234:235], v[234:235], s[60:61], 1.0 op_sel_hi:[1,0,0]
	v_pk_fma_f32 v[216:217], v[230:231], v[216:217], s[68:69] op_sel_hi:[1,1,0]
	v_rcp_f32_e32 v234, v234
	v_rcp_f32_e32 v235, v235
	v_pk_fma_f32 v[216:217], v[230:231], v[216:217], s[70:71] op_sel_hi:[1,1,0]
	v_cmp_gt_f32_e32 vcc, 0, v218
	v_pk_mul_f32 v[216:217], v[230:231], v[216:217]
	v_pk_mul_f32 v[230:231], v[218:219], v[218:219]
	v_pk_mul_f32 v[216:217], v[232:233], v[216:217]
	s_nop 0
	v_pk_mul_f32 v[232:233], v[228:229], v[216:217]
	v_pk_fma_f32 v[236:237], v[228:229], v[216:217], v[228:229] neg_lo:[1,0,0] neg_hi:[1,0,0]
	v_pk_fma_f32 v[216:217], v[234:235], s[62:63], v[226:227] op_sel_hi:[1,0,0]
	v_pk_mul_f32 v[226:227], v[230:231], s[72:73] op_sel_hi:[1,0]
	v_pk_fma_f32 v[216:217], v[234:235], v[216:217], s[66:67] op_sel_hi:[1,1,0]
	v_exp_f32_e32 v226, v226
	v_exp_f32_e32 v227, v227
	v_pk_fma_f32 v[216:217], v[234:235], v[216:217], s[68:69] op_sel_hi:[1,1,0]
	s_nop 0
	v_pk_fma_f32 v[216:217], v[234:235], v[216:217], s[70:71] op_sel_hi:[1,1,0]
	s_nop 0
	v_pk_mul_f32 v[216:217], v[234:235], v[216:217]
	s_nop 0
	v_pk_mul_f32 v[216:217], v[226:227], v[216:217]
	s_nop 0
	v_pk_mul_f32 v[226:227], v[218:219], v[216:217]
	v_pk_fma_f32 v[230:231], v[218:219], v[216:217], v[218:219] neg_lo:[1,0,0] neg_hi:[1,0,0]
	s_nop 0
	v_cndmask_b32_e32 v217, v230, v226, vcc
	v_cmp_gt_f32_e32 vcc, 0, v228
	v_cvt_pk_bf16_f32 v226, v201, v203
	s_nop 1
	v_cndmask_b32_e32 v216, v236, v232, vcc
	v_cmp_gt_f32_e32 vcc, 0, v219
	s_nop 1
	v_cndmask_b32_e32 v219, v231, v227, vcc
	v_cmp_gt_f32_e32 vcc, 0, v229
	v_cvt_pk_bf16_f32 v227, v205, v207
	s_nop 1
	v_cndmask_b32_e32 v218, v237, v233, vcc
	v_cvt_pk_bf16_f32 v228, v216, v218
	v_cvt_pk_bf16_f32 v229, v217, v219
	global_store_dwordx4 v[198:199], v[226:229], off offset:256
	s_cbranch_scc1 .LBB0_474
	v_mov_b32_e32 v209, v201
	v_mov_b32_e32 v211, v203
	v_pk_mul_f32 v[198:199], v[200:201], v[200:201]
	v_pk_mul_f32 v[226:227], v[208:209], v[208:209]
	v_pk_add_f32 v[240:241], v[200:201], v[208:209]
	v_pk_mul_f32 v[208:209], v[200:201], v[208:209]
	v_mov_b32_e32 v213, v205
	v_pk_mul_f32 v[228:229], v[202:203], v[202:203]
	v_pk_mul_f32 v[230:231], v[210:211], v[210:211]
	v_mov_b32_e32 v241, v209
	v_pk_add_f32 v[208:209], v[202:203], v[210:211]
	v_pk_mul_f32 v[210:211], v[202:203], v[210:211]
	v_pk_mov_b32 v[198:199], v[200:201], v[198:199] op_sel:[1,0]
	v_pk_mov_b32 v[200:201], v[202:203], v[226:227] op_sel:[1,0]
	v_mov_b32_e32 v215, v207
	v_pk_mul_f32 v[234:235], v[212:213], v[212:213]
	v_mov_b32_e32 v209, v211
	v_pk_add_f32 v[210:211], v[204:205], v[212:213]
	v_pk_mul_f32 v[212:213], v[204:205], v[212:213]
	v_pk_add_f32 v[198:199], v[198:199], v[200:201]
	v_pk_mov_b32 v[200:201], v[204:205], v[228:229] op_sel:[1,0]
	v_pk_mov_b32 v[202:203], v[206:207], v[230:231] op_sel:[1,0]
	v_pk_mul_f32 v[232:233], v[204:205], v[204:205]
	v_pk_mul_f32 v[238:239], v[214:215], v[214:215]
	v_mov_b32_e32 v211, v213
	v_pk_add_f32 v[212:213], v[206:207], v[214:215]
	v_pk_mul_f32 v[214:215], v[206:207], v[214:215]
	v_pk_add_f32 v[200:201], v[200:201], v[202:203]
	v_pk_mul_f32 v[236:237], v[206:207], v[206:207]
	v_mov_b32_e32 v213, v215
	v_pk_mul_f32 v[214:215], v[218:219], v[218:219]
	v_pk_add_f32 v[198:199], v[198:199], v[200:201]
	v_mov_b32_e32 v200, v216
	v_mov_b32_e32 v201, v232
	v_mov_b32_e32 v202, v218
	v_mov_b32_e32 v203, v234
	v_pk_fma_f32 v[214:215], v[216:217], v[216:217], v[214:215]
	v_pk_add_f32 v[200:201], v[200:201], v[202:203]
	v_pk_mov_b32 v[202:203], v[216:217], v[236:237] op_sel:[1,0]
	v_pk_mov_b32 v[204:205], v[218:219], v[238:239] op_sel:[1,0]
	v_pk_add_f32 v[214:215], v[214:215], v[214:215] op_sel_hi:[0,1]
	v_pk_add_f32 v[208:209], v[240:241], v[208:209]
	v_pk_add_f32 v[210:211], v[210:211], v[212:213]
	v_pk_add_f32 v[202:203], v[202:203], v[204:205]
	v_pk_add_f32 v[208:209], v[208:209], v[210:211]
	v_mov_b32_e32 v145, v215
	v_pk_add_f32 v[200:201], v[200:201], v[202:203]
	v_pk_add_f32 v[208:209], v[208:209], v[144:145]
	v_pk_add_f32 v[198:199], v[198:199], v[200:201]
	s_nop 0
	v_pk_add_f32 v[198:199], v[198:199], v[208:209]
	ds_bpermute_b32 v200, v224, v198
	ds_bpermute_b32 v201, v224, v199
	s_waitcnt lgkmcnt(0)
	v_pk_add_f32 v[198:199], v[198:199], v[200:201]
	ds_bpermute_b32 v200, v223, v198
	ds_bpermute_b32 v201, v223, v199
	s_and_saveexec_b64 s[6:7], s[2:3]
	s_cbranch_execz .LBB0_473
	v_lshl_add_u64 v[196:197], s[38:39], 0, v[196:197]
	v_lshl_add_u64 v[196:197], s[80:81], 3, v[196:197]
	s_waitcnt lgkmcnt(0)
	v_pk_add_f32 v[198:199], v[198:199], v[200:201]
	global_store_dwordx2 v[196:197], v[198:199], off
